# LN1: router-weight LDS fill as 8 wide loads in flight + ds_write_b128 (was 16 serialized load/wait/write rounds)
# baseline (speedup 1.0000x reference)
; #define LAS __attribute__((address_space(3)))
; DI void phase_ln1(KArgs args, LAS unsigned char* L, const Ctx& c) {
;     ...
;     LAS float* WR = (LAS float*)L;
;     { const float* wr = args->in[14] + (size_t)l * D * 16;
;         for (int i = c.tid; i < D * 16; i += 512) { const int col = i >> 4, e = i & 15, j = col >> 8, ln = (col >> 2) & 63, q = col & 3; WR[((j * 4 + q) * 64 + ln) * 20 + e] = wr[i]; } }
;     __syncthreads();
.LBB0_1208:
	s_andn2_b64 vcc, exec, s[0:1]
	s_cbranch_vccnz .LBB0_309
	v_mov_b32_e32 v36, v0
	s_mov_b64 s[0:1], s[80:81]
	s_load_dwordx4 s[16:19], s[0:1], 0xa0
	v_readfirstlane_b32 s3, v36
	s_mov_b32 s2, s79
	s_mov_b32 s12, s78
	v_cmp_gt_i32_e32 vcc, s88, v36
	s_and_saveexec_b64 s[4:5], vcc
	s_cbranch_execz .LBB0_1217
	s_load_dwordx2 s[6:7], s[0:1], 0x70
	v_readlane_b32 s8, v254, 16
	v_lshrrev_b32_e32 v1, 2, v36
	v_and_b32_e32 v2, 3, v1
	v_lshrrev_b32_e32 v1, 2, v1
	v_lshl_or_b32 v1, v2, 6, v1
	v_mul_u32_u24_e32 v1, 0x50, v1
	v_and_b32_e32 v2, 3, v36
	v_lshl_add_u32 v1, v2, 4, v1
	v_lshlrev_b32_e32 v2, 4, v36
	s_waitcnt lgkmcnt(0)
	s_add_u32 s6, s6, s8
	s_addc_u32 s7, s7, 0
	global_load_dwordx4 v[114:117], v2, s[6:7]
	s_add_u32 s6, s6, 0x2000
	s_addc_u32 s7, s7, 0
	global_load_dwordx4 v[118:121], v2, s[6:7]
	s_add_u32 s6, s6, 0x2000
	s_addc_u32 s7, s7, 0
	global_load_dwordx4 v[122:125], v2, s[6:7]
	s_add_u32 s6, s6, 0x2000
	s_addc_u32 s7, s7, 0
	global_load_dwordx4 v[126:129], v2, s[6:7]
	s_add_u32 s6, s6, 0x2000
	s_addc_u32 s7, s7, 0
	global_load_dwordx4 v[130:133], v2, s[6:7]
	s_add_u32 s6, s6, 0x2000
	s_addc_u32 s7, s7, 0
	global_load_dwordx4 v[134:137], v2, s[6:7]
	s_add_u32 s6, s6, 0x2000
	s_addc_u32 s7, s7, 0
	global_load_dwordx4 v[138:141], v2, s[6:7]
	s_add_u32 s6, s6, 0x2000
	s_addc_u32 s7, s7, 0
	global_load_dwordx4 v[142:145], v2, s[6:7]
	s_waitcnt vmcnt(7)
	ds_write_b128 v1, v[114:117]
	s_waitcnt vmcnt(6)
	ds_write_b128 v1, v[118:121] offset:2560
	s_waitcnt vmcnt(5)
	ds_write_b128 v1, v[122:125] offset:20480
	s_waitcnt vmcnt(4)
	ds_write_b128 v1, v[126:129] offset:23040
	s_waitcnt vmcnt(3)
	ds_write_b128 v1, v[130:133] offset:40960
	s_waitcnt vmcnt(2)
	ds_write_b128 v1, v[134:137] offset:43520
	s_waitcnt vmcnt(1)
	ds_write_b128 v1, v[138:141] offset:61440
	s_waitcnt vmcnt(0)
	ds_write_b128 v1, v[142:145] offset:64000
